# hyena: order-1 filter table loaded by helper waves 4-7 alone (all chunks in flight) while waves 0-3 run epilogue 0
# baseline (speedup 1.0000x reference)
; DI void hy_load_table(const u16* __restrict__ tbg, u16* TbE, u16* TbO, int tid) {
; #pragma unroll
;   for (int i = 0; i < 4; ++i) {
;     const int q = tid + NT * i;
;     const uint4 v = *(const uint4*)(tbg + 8 * q);
;     const unsigned nxt = (q < 2047) ? (unsigned)tbg[8 * q + 8] : 0u;
;     *(uint4*)(TbE + 8 * q) = v;
;     uint4 o;
;     o.x = (v.x >> 16) | (v.y << 16);
;     o.y = (v.y >> 16) | (v.z << 16);
;     o.z = (v.z >> 16) | (v.w << 16);
;     o.w = (v.w >> 16) | (nxt << 16);
;     *(uint4*)(TbO + 8 * q) = o;
;   }
; }
; DI void hyena_item(const P& p, int l, int c, char* smem) {
;     ...
;   hy_load_table(tbg + (size_t)512 * 16384, TbE, TbO, tid);
.LBB0_447:
	s_or_b64 exec, exec, s[78:79]
	s_add_u32 s76, s76, 0x1000000
	s_addc_u32 s77, s77, 0
	v_cmp_lt_i32_e32 vcc, 0, v250
	s_cbranch_vccnz .Lhy_t1_done
	global_load_dwordx4 v[72:75], v249, s[76:77]
	global_load_ushort v104, v249, s[76:77] offset:16
	s_add_u32 s76, s76, 0x1000
	s_addc_u32 s77, s77, 0
	global_load_dwordx4 v[76:79], v249, s[76:77]
	global_load_ushort v105, v249, s[76:77] offset:16
	s_add_u32 s76, s76, 0x1000
	s_addc_u32 s77, s77, 0
	global_load_dwordx4 v[80:83], v249, s[76:77]
	global_load_ushort v106, v249, s[76:77] offset:16
	s_add_u32 s76, s76, 0x1000
	s_addc_u32 s77, s77, 0
	global_load_dwordx4 v[84:87], v249, s[76:77]
	global_load_ushort v107, v249, s[76:77] offset:16
	s_add_u32 s76, s76, 0x1000
	s_addc_u32 s77, s77, 0
	global_load_dwordx4 v[88:91], v249, s[76:77]
	global_load_ushort v108, v249, s[76:77] offset:16
	s_add_u32 s76, s76, 0x1000
	s_addc_u32 s77, s77, 0
	global_load_dwordx4 v[92:95], v249, s[76:77]
	global_load_ushort v109, v249, s[76:77] offset:16
	s_add_u32 s76, s76, 0x1000
	s_addc_u32 s77, s77, 0
	global_load_dwordx4 v[96:99], v249, s[76:77]
	global_load_ushort v110, v249, s[76:77] offset:16
	s_add_u32 s76, s76, 0x1000
	s_addc_u32 s77, s77, 0
	global_load_dwordx4 v[100:103], v249, s[76:77]
	v_mov_b32_e32 v111, 0
	v_cmp_ne_u32_e32 vcc, 0x1ff, v198
	s_and_saveexec_b64 s[8:9], vcc
	global_load_ushort v111, v249, s[76:77] offset:16
	s_mov_b64 exec, s[8:9]
	s_waitcnt vmcnt(14)
	ds_write_b128 v249, v[72:75] offset:0
	v_alignbit_b32 v112, v73, v72, 16
	v_alignbit_b32 v113, v74, v73, 16
	v_alignbit_b32 v114, v75, v74, 16
	v_alignbit_b32 v115, v104, v75, 16
	ds_write_b128 v249, v[112:115] offset:32832
	s_waitcnt vmcnt(12)
	ds_write_b128 v249, v[76:79] offset:4096
	v_alignbit_b32 v112, v77, v76, 16
	v_alignbit_b32 v113, v78, v77, 16
	v_alignbit_b32 v114, v79, v78, 16
	v_alignbit_b32 v115, v105, v79, 16
	ds_write_b128 v249, v[112:115] offset:36928
	s_waitcnt vmcnt(10)
	ds_write_b128 v249, v[80:83] offset:8192
	v_alignbit_b32 v112, v81, v80, 16
	v_alignbit_b32 v113, v82, v81, 16
	v_alignbit_b32 v114, v83, v82, 16
	v_alignbit_b32 v115, v106, v83, 16
	ds_write_b128 v249, v[112:115] offset:41024
	s_waitcnt vmcnt(8)
	ds_write_b128 v249, v[84:87] offset:12288
	v_alignbit_b32 v112, v85, v84, 16
	v_alignbit_b32 v113, v86, v85, 16
	v_alignbit_b32 v114, v87, v86, 16
	v_alignbit_b32 v115, v107, v87, 16
	ds_write_b128 v249, v[112:115] offset:45120
	s_waitcnt vmcnt(6)
	ds_write_b128 v249, v[88:91] offset:16384
	v_alignbit_b32 v112, v89, v88, 16
	v_alignbit_b32 v113, v90, v89, 16
	v_alignbit_b32 v114, v91, v90, 16
	v_alignbit_b32 v115, v108, v91, 16
	ds_write_b128 v249, v[112:115] offset:49216
	s_waitcnt vmcnt(4)
	ds_write_b128 v249, v[92:95] offset:20480
	v_alignbit_b32 v112, v93, v92, 16
	v_alignbit_b32 v113, v94, v93, 16
	v_alignbit_b32 v114, v95, v94, 16
	v_alignbit_b32 v115, v109, v95, 16
	ds_write_b128 v249, v[112:115] offset:53312
	s_waitcnt vmcnt(2)
	ds_write_b128 v249, v[96:99] offset:24576
	v_alignbit_b32 v112, v97, v96, 16
	v_alignbit_b32 v113, v98, v97, 16
	v_alignbit_b32 v114, v99, v98, 16
	v_alignbit_b32 v115, v110, v99, 16
	ds_write_b128 v249, v[112:115] offset:57408
	s_waitcnt vmcnt(0)
	ds_write_b128 v249, v[100:103] offset:28672
	v_alignbit_b32 v112, v101, v100, 16
	v_alignbit_b32 v113, v102, v101, 16
	v_alignbit_b32 v114, v103, v102, 16
	v_alignbit_b32 v115, v111, v103, 16
	ds_write_b128 v249, v[112:115] offset:61504
; DI f32x16 zero16() { f32x16 z; for (int i = 0; i < 16; ++i) z[i] = 0.f; return z; }
; DI void hy_conv(f32x16 (&acc)[4], const u16* abase, const u16* U, const u16* Zrow, int a0, int li, int g) {
; #pragma unroll
;   for (int i = 0; i < 4; ++i) acc[i] = zero16();
;   u32x4 W[14];
;   bf16x8 bf[8];
;   int d = a0 - 63;
; #pragma unroll
;   for (int x = 0; x < 14; ++x) W[x] = hy_afrag(abase, 8 * d + x - 7);
; DI void hyena_item(const P& p, int l, int c, char* smem) {
;     ...
;   __syncthreads();
;   if (cwv) hy_conv(acc, abase, U, Zrow, a0, li, g);
.Lhy_t1_done:
	s_mov_b64 s[10:11], 0
	s_mov_b64 s[8:9], 0
	s_waitcnt lgkmcnt(0)
	s_barrier
	s_mov_b64 s[12:13], exec
	v_mov_b32_e32 v234, v228
	v_add_u32_e32 v242, 0xffffff40, v225
	v_lshlrev_b32_e32 v241, 8, v234
	v_sub_u32_e32 v240, v242, v241
	ds_read2_b32 v[72:73], v240 offset0:104 offset1:105
	ds_read2_b32 v[74:75], v240 offset0:106 offset1:107
	ds_read2_b32 v[76:77], v240 offset0:96 offset1:97
	ds_read2_b32 v[78:79], v240 offset0:98 offset1:99
	ds_read2_b32 v[80:81], v240 offset0:88 offset1:89
	ds_read2_b32 v[82:83], v240 offset0:90 offset1:91
	ds_read2_b32 v[84:85], v240 offset0:80 offset1:81
	ds_read2_b32 v[86:87], v240 offset0:82 offset1:83
	ds_read2_b32 v[88:89], v240 offset0:72 offset1:73
	ds_read2_b32 v[90:91], v240 offset0:74 offset1:75
	ds_read2_b32 v[92:93], v240 offset0:64 offset1:65
	ds_read2_b32 v[94:95], v240 offset0:66 offset1:67
	ds_read2_b32 v[96:97], v240 offset0:56 offset1:57
	ds_read2_b32 v[98:99], v240 offset0:58 offset1:59
	ds_read2_b32 v[100:101], v240 offset0:48 offset1:49
	ds_read2_b32 v[102:103], v240 offset0:50 offset1:51
	ds_read2_b32 v[104:105], v240 offset0:40 offset1:41
	ds_read2_b32 v[106:107], v240 offset0:42 offset1:43
	ds_read2_b32 v[108:109], v240 offset0:32 offset1:33
	ds_read2_b32 v[110:111], v240 offset0:34 offset1:35
	ds_read2_b32 v[112:113], v240 offset0:24 offset1:25
	ds_read2_b32 v[114:115], v240 offset0:26 offset1:27
	ds_read2_b32 v[116:117], v240 offset0:16 offset1:17
	ds_read2_b32 v[118:119], v240 offset0:18 offset1:19
	ds_read2_b32 v[120:121], v240 offset0:8 offset1:9
	ds_read2_b32 v[122:123], v240 offset0:10 offset1:11
	ds_read2_b32 v[124:125], v240 offset0:0 offset1:1
	ds_read2_b32 v[126:127], v240 offset0:2 offset1:3
	v_add_u32_e32 v241, v229, v224
	v_sub_u32_e32 v241, v241, v234
	v_mov_b32_e32 v244, s69
	v_mad_u32_u24 v236, v241, s97, v244
	v_add_u32_e32 v236, v236, v222
	v_sub_u32_e32 v235, v229, v234
	s_mov_b32 s99, 0x18880
	v_add_u32_e32 v243, s99, v222
	v_cmp_gt_u32_e32 vcc, 64, v235
	s_movk_i32 s98, 13
	v_mov_b32_e32 v0, 0
	v_cndmask_b32_e32 v237, v243, v236, vcc
	ds_read_b128 v[168:171], v237 offset:0
	ds_read_b128 v[172:175], v237 offset:32
	ds_read_b128 v[176:179], v237 offset:64
	ds_read_b128 v[180:183], v237 offset:96
	v_mov_b32_e32 v1, v0
	v_mov_b32_e32 v2, v0
	v_mov_b32_e32 v3, v0
	v_mov_b32_e32 v4, v0
	v_mov_b32_e32 v5, v0
	v_mov_b32_e32 v6, v0
	v_mov_b32_e32 v7, v0
	v_mov_b32_e32 v8, v0
	v_mov_b32_e32 v9, v0
	v_mov_b32_e32 v10, v0
	v_mov_b32_e32 v11, v0
	v_mov_b32_e32 v12, v0
	v_mov_b32_e32 v13, v0
	v_mov_b32_e32 v14, v0
	v_mov_b32_e32 v15, v0
	v_mov_b32_e32 v16, v0
	v_mov_b32_e32 v17, v0
	v_mov_b32_e32 v18, v0
	v_mov_b32_e32 v19, v0
	v_mov_b32_e32 v20, v0
	v_mov_b32_e32 v21, v0
	v_mov_b32_e32 v22, v0
	v_mov_b32_e32 v23, v0
	v_mov_b32_e32 v24, v0
	v_mov_b32_e32 v25, v0
	v_mov_b32_e32 v26, v0
	v_mov_b32_e32 v27, v0
	v_mov_b32_e32 v28, v0
	v_mov_b32_e32 v29, v0
	v_mov_b32_e32 v30, v0
	v_mov_b32_e32 v31, v0
	v_mov_b32_e32 v32, v0
	v_mov_b32_e32 v33, v0
	v_mov_b32_e32 v34, v0
	v_mov_b32_e32 v35, v0
	v_mov_b32_e32 v36, v0
	v_mov_b32_e32 v37, v0
	v_mov_b32_e32 v38, v0
	v_mov_b32_e32 v39, v0
	v_mov_b32_e32 v40, v0
	v_mov_b32_e32 v41, v0
	v_mov_b32_e32 v42, v0
	v_mov_b32_e32 v43, v0
	v_mov_b32_e32 v44, v0
	v_mov_b32_e32 v45, v0
	v_mov_b32_e32 v46, v0
	v_mov_b32_e32 v47, v0
	v_mov_b32_e32 v48, v0
	v_mov_b32_e32 v49, v0
	v_mov_b32_e32 v50, v0
	v_mov_b32_e32 v51, v0
	v_mov_b32_e32 v52, v0
	v_mov_b32_e32 v53, v0
	v_mov_b32_e32 v54, v0
	v_mov_b32_e32 v55, v0
	v_mov_b32_e32 v56, v0
	v_mov_b32_e32 v57, v0
	v_mov_b32_e32 v58, v0
	v_mov_b32_e32 v59, v0
	v_mov_b32_e32 v60, v0
	v_mov_b32_e32 v61, v0
	v_mov_b32_e32 v62, v0
	v_mov_b32_e32 v63, v0
	s_waitcnt lgkmcnt(0)
